# R1 row pass: all modulation-vector loads batched at iteration top (gpre kept in regs), counted vmcnt waits
# speedup vs baseline: 1.0112x; 1.0112x over previous
;     __device__ __forceinline__ void init(int N, int G, int c, int latent_only) { lat = latent_only; b.init(latent_only ? NB * SEQ : M, N, G, c); }
;     __device__ __forceinline__ void init(int c_, unsigned* cnt_) { lat.init(NB * SEQ, FF2, 1, 0); c = c_; cnt = cnt_; }
; __device__ __forceinline__ void row_pass(const RowPass& R, int gw, int ngw, int lane) {
;     constexpr int NR = 2;
;     for (int row0 = gw; row0 < M; row0 += NR * ngw) {
;         f32x4 v[NR][4]; u32x2 yw[NR][4]; bool act[NR]; float* xrow[NR]; int bbs[NR];
; #pragma unroll
;         for (int k = 0; k < NR; ++k) {
;             const int row = row0 + k * ngw;
;             const int rowc = row < M ? row : row0;
;             const int b = rowc / RPB, i = rowc - b * RPB; const bool isctx = i < CTXL;
;             act[k] = (row < M) && !(isctx && R.skip_ctx);
;             bbs[k] = isctx ? 8 : b;
;             xrow[k] = isctx ? R.xc + ((size_t)b * CTXL + i) * DM : R.out + ((size_t)b * SEQ + (i - CTXL)) * DM;
;             const float* src = R.init ? (isctx ? R.ctx_in + ((size_t)b * CTXL + i) * DM : R.x_in + ((size_t)b * SEQ + (i - CTXL)) * DM) : xrow[k];
;             if (act[k]) {
; #pragma unroll
;                 for (int j = 0; j < 4; ++j) v[k][j] = __builtin_nontemporal_load((const f32x4*)(src + lane * 4 + 256 * j));
;     ...
;                 for (int j = 0; j < 4; ++j) { const f32x4 gp = *(const f32x4*)(R.gpre + lane * 4 + 256 * j), sh = *(const f32x4*)(shift + lane * 4 + 256 * j), sc = *(const f32x4*)(scale + lane * 4 + 256 * j);
.LBB0_364:
	s_and_b64 vcc, exec, s[4:5]
	s_mov_b32 s52, 0xb00000
	s_cbranch_vccz .LBB0_372
	s_cmp_gt_i32 s36, 0x87ff
	s_cbranch_scc1 .LBB0_372
	s_load_dwordx2 s[4:5], s[0:1], 0x0
	s_load_dwordx2 s[6:7], s[0:1], 0x10
	s_load_dwordx2 s[10:11], s[0:1], 0x30
	s_load_dwordx2 s[8:9], s[0:1], 0xa0
	v_cmp_lt_i32_e32 vcc, v205, v204
	v_lshlrev_b32_e32 v160, 4, v216
	s_ashr_i32 s37, s36, 31
	s_waitcnt vmcnt(0)
	v_cndmask_b32_e32 v0, v203, v205, vcc
	v_cmp_lt_i32_e32 vcc, v206, v204
	s_waitcnt lgkmcnt(0)
	v_lshl_add_u64 v[34:35], s[10:11], 0, v[160:161]
	global_load_dwordx4 v[238:241], v[34:35], off
	global_load_dwordx4 v[242:245], v[34:35], off offset:1024
	global_load_dwordx4 v[246:249], v[34:35], off offset:2048
	global_load_dwordx4 v[250:253], v[34:35], off offset:3072
	s_lshl_b64 s[10:11], s[36:37], 11
	v_lshlrev_b32_e32 v33, 2, v0
	v_cndmask_b32_e32 v0, v203, v206, vcc
	v_cmp_lt_i32_e32 vcc, v207, v204
	s_add_u32 s10, s28, s10
	v_readlane_b32 s3, v254, 63
	v_lshlrev_b32_e32 v38, 2, v0
	v_cndmask_b32_e32 v0, v203, v207, vcc
	v_cmp_lt_i32_e32 vcc, v208, v204
	s_addc_u32 s11, s29, s11
	s_add_i32 s12, s3, s12
	v_lshlrev_b32_e32 v39, 2, v0
	v_cndmask_b32_e32 v0, v203, v208, vcc
	v_cmp_lt_i32_e32 vcc, v209, v204
	s_ashr_i32 s13, s12, 31
	v_lshlrev_b32_e32 v40, 2, v0
	v_cndmask_b32_e32 v0, v203, v209, vcc
	v_cmp_lt_i32_e32 vcc, v210, v204
	s_lshl_b64 s[12:13], s[12:13], 11
	v_lshlrev_b32_e32 v41, 2, v0
	v_cndmask_b32_e32 v0, v203, v210, vcc
	s_add_u32 s12, s28, s12
	v_lshlrev_b32_e32 v32, 2, v216
	v_lshlrev_b32_e32 v42, 2, v0
	v_lshlrev_b32_e32 v36, 3, v216
	v_mov_b32_e32 v37, v161
	s_addc_u32 s13, s29, s13
	s_branch .LBB0_368

; __device__ __forceinline__ void row_pass(const RowPass& R, int gw, int ngw, int lane) {
;     ...
;     for (int row0 = gw; row0 < M; row0 += NR * ngw) {
;         f32x4 v[NR][4]; u32x2 yw[NR][4]; bool act[NR]; float* xrow[NR]; int bbs[NR];
; #pragma unroll
;         for (int k = 0; k < NR; ++k) {
;             const int row = row0 + k * ngw;
;             const int rowc = row < M ? row : row0;
;             const int b = rowc / RPB, i = rowc - b * RPB; const bool isctx = i < CTXL;
;             act[k] = (row < M) && !(isctx && R.skip_ctx);
;             bbs[k] = isctx ? 8 : b;
;             xrow[k] = isctx ? R.xc + ((size_t)b * CTXL + i) * DM : R.out + ((size_t)b * SEQ + (i - CTXL)) * DM;
;             const float* src = R.init ? (isctx ? R.ctx_in + ((size_t)b * CTXL + i) * DM : R.x_in + ((size_t)b * SEQ + (i - CTXL)) * DM) : xrow[k];
;             if (act[k]) {
; #pragma unroll
;                 for (int j = 0; j < 4; ++j) v[k][j] = __builtin_nontemporal_load((const f32x4*)(src + lane * 4 + 256 * j));
;                 if (R.update) { const bf16* yr = R.Y + (size_t)rowc * DM;
; #pragma unroll
;                     for (int j = 0; j < 4; ++j) yw[k][j] = __builtin_nontemporal_load((const u32x2*)(yr + lane * 4 + 256 * j)); }
;             }
;         }
; #pragma unroll
;         for (int k = 0; k < NR; ++k) {
;             if (!act[k]) continue;
;             const int row = row0 + k * ngw, bb = bbs[k];
;             if (R.update) {
;                 f32x4 y[4]; float ss = 0.f;
; #pragma unroll
;                 for (int j = 0; j < 4; ++j) { const u32x2 w = yw[k][j]; y[j] = (f32x4){bflo(w.x), bfhi(w.x), bflo(w.y), bfhi(w.y)};
;                     ss += (y[j][0] * y[j][0] + y[j][1] * y[j][1]) + (y[j][2] * y[j][2] + y[j][3] * y[j][3]); }
;                 const float rstd = __builtin_amdgcn_rsqf(wave_sum(ss) * (1.0f / DM) + EPS);
;                 const float* gate = R.mod + ((size_t)(R.lg * 9 + bb) * NMOD + R.gi) * DM;
; #pragma unroll
;                 for (int j = 0; j < 4; ++j) { const f32x4 g = *(const f32x4*)(gate + lane * 4 + 256 * j), gp = *(const f32x4*)(R.gpost + lane * 4 + 256 * j);
;                     v[k][j] = v[k][j] + g * (y[j] * rstd * gp); }
;             }
;             if (R.init || R.update) {
; #pragma unroll
;                 for (int j = 0; j < 4; ++j) __builtin_nontemporal_store(v[k][j], (f32x4*)(xrow[k] + lane * 4 + 256 * j));
.LBB0_368:
	s_mul_hi_i32 s3, s36, 0x78787879
	s_lshr_b32 s14, s3, 31
	s_ashr_i32 s3, s3, 11
	s_add_i32 s38, s3, s14
	s_mul_i32 s3, s38, 0xffffef00
	s_add_i32 s3, s36, s3
	s_cmpk_gt_i32 s3, 0xff
	s_cselect_b64 s[40:41], -1, 0
	s_ashr_i32 s39, s38, 31
	s_add_i32 s16, s3, 0xffffff00
	s_ashr_i32 s17, s3, 31
	s_and_b64 s[14:15], s[40:41], exec
	s_cselect_b32 s15, 0, s17
	s_cselect_b32 s14, s16, s3
	s_cselect_b32 s3, 24, 20
	s_lshl_b64 s[60:61], s[38:39], s3
	s_lshl_b64 s[50:51], s[14:15], 12
	s_and_b64 s[14:15], s[40:41], exec
	s_cselect_b32 s14, s4, s6
	s_cselect_b32 s3, s5, s7
	s_add_u32 s14, s14, s60
	s_addc_u32 s3, s3, s61
	s_add_u32 s14, s14, s50
	s_addc_u32 s15, s3, s51
	v_lshlrev_b32_e32 v160, 2, v32
	global_load_dwordx4 v[28:31], v160, s[14:15] nt
	global_load_dwordx4 v[24:27], v160, s[14:15] offset:1024 nt
	global_load_dwordx4 v[20:23], v160, s[14:15] offset:2048 nt
	global_load_dwordx4 v[16:19], v160, s[14:15] offset:3072 nt
	s_add_i32 s3, s44, s36
	s_cmp_lt_i32 s3, 0x8800
	s_cselect_b64 s[20:21], -1, 0
	s_and_b64 s[14:15], s[20:21], exec
	s_cselect_b32 s15, s3, s36
	s_mul_hi_i32 s14, s15, 0x78787879
	s_lshr_b32 s16, s14, 31
	s_ashr_i32 s14, s14, 11
	s_add_i32 s14, s14, s16
	s_mul_i32 s16, s14, 0xffffef00
	s_add_i32 s19, s16, s15
	s_cmpk_gt_i32 s19, 0xff
	s_cselect_b64 s[16:17], -1, 0
	s_ashr_i32 s15, s14, 31
	s_add_i32 s25, s19, 0xffffff00
	s_ashr_i32 s26, s19, 31
	s_and_b64 s[22:23], s[16:17], exec
	s_cselect_b32 s23, 0, s26
	s_cselect_b32 s22, s25, s19
	s_cselect_b32 s19, 24, 20
	s_lshl_b64 s[26:27], s[14:15], s19
	s_lshl_b64 s[22:23], s[22:23], 12
	s_and_b64 s[46:47], s[16:17], exec
	s_cselect_b32 s15, s4, s6
	s_cselect_b32 s3, s5, s7
	s_add_u32 s15, s15, s26
	s_addc_u32 s3, s3, s27
	s_add_u32 s46, s15, s22
	s_addc_u32 s47, s3, s23
	global_load_dwordx4 v[0:3], v160, s[46:47] nt
	global_load_dwordx4 v[4:7], v160, s[46:47] offset:1024 nt
	global_load_dwordx4 v[8:11], v160, s[46:47] offset:2048 nt
	global_load_dwordx4 v[12:15], v160, s[46:47] offset:3072 nt
.LBB0_370:
	s_and_b64 s[46:47], s[40:41], exec
	s_cselect_b32 s15, s8, s49
	s_cselect_b32 s3, s9, s55
	s_add_u32 s15, s15, s60
	s_addc_u32 s3, s3, s61
	s_add_u32 s46, s15, s50
	s_addc_u32 s47, s3, s51
	s_mul_i32 s3, s38, 6
	s_and_b64 s[38:39], s[40:41], exec
	s_cselect_b32 s38, s3, 48
	s_ashr_i32 s39, s38, 31
	s_lshl_b64 s[38:39], s[38:39], 12
	s_add_u32 s38, s34, s38
	s_addc_u32 s39, s35, s39
	s_add_u32 s84, s38, 0x1000
	s_addc_u32 s85, s39, 0
	global_load_dwordx4 v[172:175], v160, s[84:85]
	global_load_dwordx4 v[176:179], v160, s[38:39]
	global_load_dwordx4 v[180:183], v160, s[84:85] offset:1024
	global_load_dwordx4 v[184:187], v160, s[38:39] offset:1024
	global_load_dwordx4 v[188:191], v160, s[84:85] offset:2048
	global_load_dwordx4 v[192:195], v160, s[38:39] offset:2048
	global_load_dwordx4 v[196:199], v160, s[84:85] offset:3072
	global_load_dwordx4 v[218:221], v160, s[38:39] offset:3072
	s_and_b64 s[64:65], s[16:17], exec
	s_cselect_b32 s25, s8, s49
	s_cselect_b32 s3, s9, s55
	s_add_u32 s25, s25, s26
	s_addc_u32 s3, s3, s27
	s_add_u32 s64, s25, s22
	s_addc_u32 s65, s3, s23
	s_mul_i32 s3, s14, 6
	s_and_b64 s[62:63], s[16:17], exec
	s_cselect_b32 s62, s3, 48
	s_ashr_i32 s63, s62, 31
	s_lshl_b64 s[62:63], s[62:63], 12
	s_add_u32 s62, s34, s62
	s_addc_u32 s63, s35, s63
	s_add_u32 s60, s62, 0x1000
	s_addc_u32 s61, s63, 0
	global_load_dwordx4 v[222:225], v160, s[60:61]
	global_load_dwordx4 v[226:229], v160, s[62:63]
	global_load_dwordx4 v[230:233], v160, s[60:61] offset:1024
	global_load_dwordx4 v[234:237], v160, s[62:63] offset:1024
	global_load_dwordx4 v[44:47], v160, s[60:61] offset:2048
	global_load_dwordx4 v[48:51], v160, s[62:63] offset:2048
	global_load_dwordx4 v[52:55], v160, s[60:61] offset:3072
	global_load_dwordx4 v[164:167], v160, s[62:63] offset:3072
	s_waitcnt vmcnt(23)
	global_store_dwordx4 v160, v[28:31], s[46:47] nt
	s_waitcnt vmcnt(23)
	global_store_dwordx4 v160, v[24:27], s[46:47] offset:1024 nt
	s_waitcnt vmcnt(23)
	global_store_dwordx4 v160, v[20:23], s[46:47] offset:2048 nt
	s_waitcnt vmcnt(23)
	global_store_dwordx4 v160, v[16:19], s[46:47] offset:3072 nt
	v_pk_mul_f32 v[58:59], v[30:31], v[30:31]
	v_pk_mul_f32 v[60:61], v[28:29], v[28:29]
	v_mul_f32_e32 v43, v16, v16
	v_pk_mov_b32 v[62:63], v[60:61], v[58:59] op_sel:[1,0]
	v_mov_b32_e32 v61, v59
	v_pk_add_f32 v[58:59], v[62:63], v[60:61]
	v_pk_mul_f32 v[60:61], v[26:27], v[26:27]
	v_pk_mul_f32 v[62:63], v[24:25], v[24:25]
	v_pk_add_f32 v[58:59], v[58:59], v[58:59] op_sel:[0,1] op_sel_hi:[1,0]
	v_pk_mov_b32 v[64:65], v[62:63], v[60:61] op_sel:[1,0]
	v_mov_b32_e32 v63, v61
	v_pk_add_f32 v[60:61], v[64:65], v[62:63]
	v_mul_f32_e32 v62, v17, v17
	v_pk_add_f32 v[60:61], v[60:61], v[60:61] op_sel:[0,1] op_sel_hi:[1,0]
	v_mov_b32_e32 v59, v43
	v_mov_b32_e32 v61, v62
	v_pk_add_f32 v[58:59], v[58:59], v[60:61]
	v_mul_f32_e32 v60, v21, v21
	v_mul_f32_e32 v63, v18, v18
	v_pk_fma_f32 v[60:61], v[20:21], v[20:21], v[60:61] op_sel_hi:[1,1,0]
	v_mul_f32_e32 v62, v23, v23
	v_mul_f32_e32 v64, v19, v19
	v_mov_b32_e32 v61, v63
	v_pk_fma_f32 v[62:63], v[22:23], v[22:23], v[62:63] op_sel_hi:[1,1,0]
	s_nop 0
	v_mov_b32_e32 v63, v64
	v_pk_add_f32 v[60:61], v[60:61], v[62:63]
	s_nop 0
	v_pk_add_f32 v[58:59], v[58:59], v[60:61]
	s_nop 0
	v_add_f32_e32 v43, v58, v59
	ds_bpermute_b32 v58, v33, v43
	s_waitcnt lgkmcnt(0)
	v_add_f32_e32 v43, v43, v58
	ds_bpermute_b32 v58, v38, v43
	s_waitcnt lgkmcnt(0)
	v_add_f32_e32 v43, v43, v58
	ds_bpermute_b32 v58, v39, v43
	s_waitcnt lgkmcnt(0)
	v_add_f32_e32 v43, v43, v58
	ds_bpermute_b32 v58, v40, v43
	s_waitcnt lgkmcnt(0)
	v_add_f32_e32 v43, v43, v58
	ds_bpermute_b32 v58, v41, v43
	s_waitcnt lgkmcnt(0)
; __device__ __forceinline__ unsigned pk2(float lo, float hi) { return pg8::cvt_pk_bf16(lo, hi); }
; __device__ __forceinline__ void row_pass(const RowPass& R, int gw, int ngw, int lane) {
;     ...
;             if (R.norm_out) {
;                 float ss = 0.f;
; #pragma unroll
;                 for (int j = 0; j < 4; ++j) ss += (v[k][j][0] * v[k][j][0] + v[k][j][1] * v[k][j][1]) + (v[k][j][2] * v[k][j][2] + v[k][j][3] * v[k][j][3]);
;                 const float rstd = __builtin_amdgcn_rsqf(wave_sum(ss) * (1.0f / DM) + EPS);
;                 const float* shift = R.mod + ((size_t)(R.ln * 9 + bb) * NMOD + R.si) * DM; const float* scale = shift + DM;
;                 bf16* hr = R.H + (size_t)row * DM;
; #pragma unroll
;                 for (int j = 0; j < 4; ++j) { const f32x4 gp = *(const f32x4*)(R.gpre + lane * 4 + 256 * j), sh = *(const f32x4*)(shift + lane * 4 + 256 * j), sc = *(const f32x4*)(scale + lane * 4 + 256 * j);
;                     const f32x4 hv = (v[k][j] * rstd * gp) * (sc + 1.0f) + sh;
;                     u32x2 w; w.x = pk2(hv[0], hv[1]); w.y = pk2(hv[2], hv[3]); *(u32x2*)(hr + lane * 4 + 256 * j) = w; }
;             }
	v_add_f32_e32 v43, v43, v58
	ds_bpermute_b32 v60, v42, v43
	v_lshl_add_u64 v[58:59], s[10:11], 0, v[36:37]
	v_add_co_u32_e32 v58, vcc, s95, v58
	s_waitcnt lgkmcnt(0)
	v_add_f32_e32 v43, v43, v60
	v_fmamk_f32 v43, v43, 0x3a800000, v200
	v_rsq_f32_e32 v60, v43
	v_addc_co_u32_e32 v59, vcc, 0, v59, vcc
	s_andn2_b64 vcc, exec, s[20:21]
	v_pk_mul_f32 v[28:29], v[28:29], v[60:61] op_sel_hi:[1,0]
	v_pk_mul_f32 v[30:31], v[30:31], v[60:61] op_sel_hi:[1,0]
	v_pk_mul_f32 v[28:29], v[238:239], v[28:29]
	v_pk_mul_f32 v[30:31], v[240:241], v[30:31]
	s_waitcnt vmcnt(18)
	v_pk_add_f32 v[172:173], v[172:173], 1.0 op_sel_hi:[1,0]
	v_pk_add_f32 v[174:175], v[174:175], 1.0 op_sel_hi:[1,0]
	v_pk_fma_f32 v[28:29], v[172:173], v[28:29], v[176:177]
	v_pk_fma_f32 v[30:31], v[174:175], v[30:31], v[178:179]
	v_cvt_pk_bf16_f32 v28, v28, v29
	s_nop 0
	v_cvt_pk_bf16_f32 v29, v30, v31
	global_store_dwordx2 v[58:59], v[28:29], off
	v_pk_mul_f32 v[24:25], v[24:25], v[60:61] op_sel_hi:[1,0]
	v_pk_mul_f32 v[26:27], v[26:27], v[60:61] op_sel_hi:[1,0]
	v_pk_mul_f32 v[24:25], v[242:243], v[24:25]
	v_pk_mul_f32 v[26:27], v[244:245], v[26:27]
	s_waitcnt vmcnt(17)
	v_pk_add_f32 v[180:181], v[180:181], 1.0 op_sel_hi:[1,0]
	v_pk_add_f32 v[182:183], v[182:183], 1.0 op_sel_hi:[1,0]
	v_pk_fma_f32 v[24:25], v[180:181], v[24:25], v[184:185]
	v_pk_fma_f32 v[26:27], v[182:183], v[26:27], v[186:187]
	v_cvt_pk_bf16_f32 v24, v24, v25
	s_nop 0
	v_cvt_pk_bf16_f32 v25, v26, v27
	global_store_dwordx2 v[58:59], v[24:25], off offset:512
	v_pk_mul_f32 v[20:21], v[20:21], v[60:61] op_sel_hi:[1,0]
	v_pk_mul_f32 v[22:23], v[22:23], v[60:61] op_sel_hi:[1,0]
	v_pk_mul_f32 v[20:21], v[246:247], v[20:21]
	v_pk_mul_f32 v[22:23], v[248:249], v[22:23]
	s_waitcnt vmcnt(16)
	v_pk_add_f32 v[188:189], v[188:189], 1.0 op_sel_hi:[1,0]
	v_pk_add_f32 v[190:191], v[190:191], 1.0 op_sel_hi:[1,0]
	v_pk_fma_f32 v[20:21], v[188:189], v[20:21], v[192:193]
	v_pk_fma_f32 v[22:23], v[190:191], v[22:23], v[194:195]
	v_cvt_pk_bf16_f32 v20, v20, v21
	s_nop 0
	v_cvt_pk_bf16_f32 v21, v22, v23
	global_store_dwordx2 v[58:59], v[20:21], off offset:1024
	v_pk_mul_f32 v[16:17], v[16:17], v[60:61] op_sel_hi:[1,0]
	v_pk_mul_f32 v[18:19], v[18:19], v[60:61] op_sel_hi:[1,0]
	v_pk_mul_f32 v[16:17], v[250:251], v[16:17]
	v_pk_mul_f32 v[18:19], v[252:253], v[18:19]
	s_waitcnt vmcnt(15)
	v_pk_add_f32 v[196:197], v[196:197], 1.0 op_sel_hi:[1,0]
	v_pk_add_f32 v[198:199], v[198:199], 1.0 op_sel_hi:[1,0]
	v_pk_fma_f32 v[16:17], v[196:197], v[16:17], v[218:219]
	v_pk_fma_f32 v[18:19], v[198:199], v[18:19], v[220:221]
	v_cvt_pk_bf16_f32 v16, v16, v17
	s_nop 0
	v_cvt_pk_bf16_f32 v17, v18, v19
	global_store_dwordx2 v[58:59], v[16:17], off offset:1536
	s_cbranch_vccnz .Lr1_binv
	global_store_dwordx4 v160, v[0:3], s[64:65] nt
	global_store_dwordx4 v160, v[4:7], s[64:65] offset:1024 nt
	global_store_dwordx4 v160, v[8:11], s[64:65] offset:2048 nt
	global_store_dwordx4 v160, v[12:15], s[64:65] offset:3072 nt
	v_pk_mul_f32 v[58:59], v[2:3], v[2:3]
	v_pk_mul_f32 v[60:61], v[0:1], v[0:1]
	v_mul_f32_e32 v43, v12, v12
	v_pk_mov_b32 v[62:63], v[60:61], v[58:59] op_sel:[1,0]
	v_mov_b32_e32 v61, v59
	v_pk_add_f32 v[58:59], v[62:63], v[60:61]
	v_pk_mul_f32 v[60:61], v[6:7], v[6:7]
	v_pk_mul_f32 v[62:63], v[4:5], v[4:5]
	v_pk_add_f32 v[58:59], v[58:59], v[58:59] op_sel:[0,1] op_sel_hi:[1,0]
	v_pk_mov_b32 v[64:65], v[62:63], v[60:61] op_sel:[1,0]
	v_mov_b32_e32 v63, v61
	v_pk_add_f32 v[60:61], v[64:65], v[62:63]
	v_mul_f32_e32 v62, v13, v13
	v_pk_add_f32 v[60:61], v[60:61], v[60:61] op_sel:[0,1] op_sel_hi:[1,0]
	v_mov_b32_e32 v59, v43
	v_mov_b32_e32 v61, v62
	v_pk_add_f32 v[58:59], v[58:59], v[60:61]
	v_mul_f32_e32 v60, v9, v9
	v_mul_f32_e32 v63, v14, v14
	v_pk_fma_f32 v[60:61], v[8:9], v[8:9], v[60:61] op_sel_hi:[1,1,0]
	v_mul_f32_e32 v62, v11, v11
	v_mul_f32_e32 v64, v15, v15
	v_mov_b32_e32 v61, v63
	v_pk_fma_f32 v[62:63], v[10:11], v[10:11], v[62:63] op_sel_hi:[1,1,0]
	s_nop 0
	v_mov_b32_e32 v63, v64
	v_pk_add_f32 v[60:61], v[60:61], v[62:63]
	s_nop 0
	v_pk_add_f32 v[58:59], v[58:59], v[60:61]
	s_nop 0
	v_add_f32_e32 v43, v58, v59
	ds_bpermute_b32 v58, v33, v43
	s_waitcnt lgkmcnt(0)
	v_add_f32_e32 v43, v43, v58
	ds_bpermute_b32 v58, v38, v43
	s_waitcnt lgkmcnt(0)
	v_add_f32_e32 v43, v43, v58
	ds_bpermute_b32 v58, v39, v43
	s_waitcnt lgkmcnt(0)
	v_add_f32_e32 v43, v43, v58
	ds_bpermute_b32 v58, v40, v43
	s_waitcnt lgkmcnt(0)
	v_add_f32_e32 v43, v43, v58
	ds_bpermute_b32 v58, v41, v43
	s_waitcnt lgkmcnt(0)
	v_add_f32_e32 v43, v43, v58
	ds_bpermute_b32 v60, v42, v43
	v_lshl_add_u64 v[58:59], s[12:13], 0, v[36:37]
	v_add_co_u32_e32 v58, vcc, s95, v58
	s_waitcnt lgkmcnt(0)
	v_add_f32_e32 v43, v43, v60
	v_fmamk_f32 v43, v43, 0x3a800000, v200
	v_rsq_f32_e32 v60, v43
	v_addc_co_u32_e32 v59, vcc, 0, v59, vcc
	s_nop 0
	v_pk_mul_f32 v[0:1], v[0:1], v[60:61] op_sel_hi:[1,0]
	v_pk_mul_f32 v[2:3], v[2:3], v[60:61] op_sel_hi:[1,0]
	v_pk_mul_f32 v[0:1], v[238:239], v[0:1]
	v_pk_mul_f32 v[2:3], v[240:241], v[2:3]
	s_waitcnt vmcnt(18)
	v_pk_add_f32 v[222:223], v[222:223], 1.0 op_sel_hi:[1,0]
	v_pk_add_f32 v[224:225], v[224:225], 1.0 op_sel_hi:[1,0]
	v_pk_fma_f32 v[0:1], v[222:223], v[0:1], v[226:227]
	v_pk_fma_f32 v[2:3], v[224:225], v[2:3], v[228:229]
	v_cvt_pk_bf16_f32 v0, v0, v1
	s_nop 0
	v_cvt_pk_bf16_f32 v1, v2, v3
	global_store_dwordx2 v[58:59], v[0:1], off
	v_pk_mul_f32 v[4:5], v[4:5], v[60:61] op_sel_hi:[1,0]
	v_pk_mul_f32 v[6:7], v[6:7], v[60:61] op_sel_hi:[1,0]
	v_pk_mul_f32 v[4:5], v[242:243], v[4:5]
	v_pk_mul_f32 v[6:7], v[244:245], v[6:7]
	s_waitcnt vmcnt(17)
	v_pk_add_f32 v[230:231], v[230:231], 1.0 op_sel_hi:[1,0]
	v_pk_add_f32 v[232:233], v[232:233], 1.0 op_sel_hi:[1,0]
	v_pk_fma_f32 v[4:5], v[230:231], v[4:5], v[234:235]
	v_pk_fma_f32 v[6:7], v[232:233], v[6:7], v[236:237]
	v_cvt_pk_bf16_f32 v4, v4, v5
	s_nop 0
	v_cvt_pk_bf16_f32 v5, v6, v7
	global_store_dwordx2 v[58:59], v[4:5], off offset:512
	v_pk_mul_f32 v[8:9], v[8:9], v[60:61] op_sel_hi:[1,0]
	v_pk_mul_f32 v[10:11], v[10:11], v[60:61] op_sel_hi:[1,0]
	v_pk_mul_f32 v[8:9], v[246:247], v[8:9]
	v_pk_mul_f32 v[10:11], v[248:249], v[10:11]
	s_waitcnt vmcnt(16)
	v_pk_add_f32 v[44:45], v[44:45], 1.0 op_sel_hi:[1,0]
	v_pk_add_f32 v[46:47], v[46:47], 1.0 op_sel_hi:[1,0]
	v_pk_fma_f32 v[8:9], v[44:45], v[8:9], v[48:49]
	v_pk_fma_f32 v[10:11], v[46:47], v[10:11], v[50:51]
	v_cvt_pk_bf16_f32 v8, v8, v9
	s_nop 0
	v_cvt_pk_bf16_f32 v9, v10, v11
	global_store_dwordx2 v[58:59], v[8:9], off offset:1024
	v_pk_mul_f32 v[12:13], v[12:13], v[60:61] op_sel_hi:[1,0]
	v_pk_mul_f32 v[14:15], v[14:15], v[60:61] op_sel_hi:[1,0]
	v_pk_mul_f32 v[12:13], v[250:251], v[12:13]
	v_pk_mul_f32 v[14:15], v[252:253], v[14:15]
	s_waitcnt vmcnt(15)
	v_pk_add_f32 v[52:53], v[52:53], 1.0 op_sel_hi:[1,0]
	v_pk_add_f32 v[54:55], v[54:55], 1.0 op_sel_hi:[1,0]
	v_pk_fma_f32 v[12:13], v[52:53], v[12:13], v[164:165]
	v_pk_fma_f32 v[14:15], v[54:55], v[14:15], v[166:167]
	v_cvt_pk_bf16_f32 v12, v12, v13
	s_nop 0
	v_cvt_pk_bf16_f32 v13, v14, v15
	global_store_dwordx2 v[58:59], v[12:13], off offset:1536
	s_branch .LBB0_367
